# v2 + K-loop LDS-DMA pieces addressed as SGPR base + 32-bit VGPR offset (no per-piece 64-bit VALU add), m0 wait states filled with ds_reads, in all four GEMM phases
# speedup vs baseline: 1.0064x; 1.0064x over previous
.LBB0_249:
	s_lshl_b32 s2, s87, 7
	s_add_u32 s12, s84, s2
	s_addc_u32 s13, s85, 0
	s_add_u32 s4, s12, 0x100
	s_addc_u32 s5, s13, 0
	s_and_b64 s[2:3], s[92:93], exec
	v_add_u32_e32 v140, s0, v1
	s_mul_i32 s2, s87, 0x188800
	ds_read_b128 v[148:151], v140
	ds_read_b128 v[152:155], v140 offset:256
	ds_read_b128 v[156:159], v140 offset:8192
	ds_read_b128 v[160:163], v140 offset:8448
	v_add_u32_e32 v140, s1, v1
	s_cselect_b32 s5, s5, s81
	s_cselect_b32 s4, s4, s80
	s_add_u32 s2, s88, s2
	ds_read_b128 v[164:167], v140
	ds_read_b128 v[168:171], v140 offset:256
	ds_read_b128 v[172:175], v140 offset:8192
	ds_read_b128 v[176:179], v140 offset:8448
	s_addc_u32 s3, s89, 0
	s_add_u32 s20, s2, 0x311000
	s_addc_u32 s21, s3, 0
	s_and_b64 s[2:3], s[92:93], exec
	s_cselect_b32 s92, s20, s86
	s_cselect_b32 s93, s21, s75
	s_add_u32 s94, s92, 0x188800
	s_addc_u32 s95, s93, 0
	s_add_u32 s98, s92, s10
	s_addc_u32 s99, s93, s11
	s_add_u32 s100, s4, s52
	s_addc_u32 s101, s5, s53
	s_add_u32 s2, s12, 0x104080
	s_addc_u32 s3, s13, 0
	s_add_i32 m0, s68, 0xc000
	ds_read_b128 v[180:183], v145
	ds_read_b128 v[184:187], v145 offset:1024
	ds_read_b128 v[188:191], v145 offset:2048
	ds_read_b128 v[192:195], v145 offset:3072
	ds_read_b128 v[196:199], v145 offset:4096
	ds_read_b128 v[200:203], v145 offset:5120
	ds_read_b128 v[204:207], v145 offset:6144
	global_load_lds_dwordx4 v130, s[2:3]
	s_add_i32 m0, s68, 0xe000
	ds_read_b128 v[208:211], v145 offset:7168
	global_load_lds_dwordx4 v134, s[2:3]
	s_waitcnt vmcnt(8)
	s_waitcnt lgkmcnt(0)
	s_barrier
	s_setprio 1
	s_waitcnt lgkmcnt(0)
	v_mfma_f32_16x16x32_bf16 v[126:129], v[148:151], v[180:183], v[126:129]
	v_mfma_f32_16x16x32_bf16 v[122:125], v[152:155], v[180:183], v[122:125]
	v_mfma_f32_16x16x32_bf16 v[118:121], v[148:151], v[188:191], v[118:121]
	v_mfma_f32_16x16x32_bf16 v[110:113], v[152:155], v[188:191], v[110:113]
	v_mfma_f32_16x16x32_bf16 v[102:105], v[148:151], v[196:199], v[102:105]
	v_mfma_f32_16x16x32_bf16 v[94:97], v[152:155], v[196:199], v[94:97]
	v_mfma_f32_16x16x32_bf16 v[86:89], v[148:151], v[204:207], v[86:89]
	v_mfma_f32_16x16x32_bf16 v[78:81], v[152:155], v[204:207], v[78:81]
	v_mfma_f32_16x16x32_bf16 v[126:129], v[156:159], v[184:187], v[126:129]
	v_mfma_f32_16x16x32_bf16 v[122:125], v[160:163], v[184:187], v[122:125]
	v_mfma_f32_16x16x32_bf16 v[118:121], v[156:159], v[192:195], v[118:121]
	v_mfma_f32_16x16x32_bf16 v[110:113], v[160:163], v[192:195], v[110:113]
	v_mfma_f32_16x16x32_bf16 v[102:105], v[156:159], v[200:203], v[102:105]
	v_mfma_f32_16x16x32_bf16 v[94:97], v[160:163], v[200:203], v[94:97]
	v_mfma_f32_16x16x32_bf16 v[86:89], v[156:159], v[208:211], v[86:89]
	v_mfma_f32_16x16x32_bf16 v[78:81], v[160:163], v[208:211], v[78:81]
	s_setprio 0
	s_setprio 1
	v_mfma_f32_16x16x32_bf16 v[114:117], v[164:167], v[180:183], v[114:117]
	v_mfma_f32_16x16x32_bf16 v[106:109], v[168:171], v[180:183], v[106:109]
	v_mfma_f32_16x16x32_bf16 v[98:101], v[164:167], v[188:191], v[98:101]
	v_mfma_f32_16x16x32_bf16 v[90:93], v[168:171], v[188:191], v[90:93]
	v_mfma_f32_16x16x32_bf16 v[82:85], v[164:167], v[196:199], v[82:85]
	v_mfma_f32_16x16x32_bf16 v[74:77], v[168:171], v[196:199], v[74:77]
	v_mfma_f32_16x16x32_bf16 v[70:73], v[164:167], v[204:207], v[70:73]
	v_mfma_f32_16x16x32_bf16 v[66:69], v[168:171], v[204:207], v[66:69]
	v_mfma_f32_16x16x32_bf16 v[114:117], v[172:175], v[184:187], v[114:117]
	v_mfma_f32_16x16x32_bf16 v[106:109], v[176:179], v[184:187], v[106:109]
	v_mfma_f32_16x16x32_bf16 v[98:101], v[172:175], v[192:195], v[98:101]
	v_mfma_f32_16x16x32_bf16 v[90:93], v[176:179], v[192:195], v[90:93]
	v_mfma_f32_16x16x32_bf16 v[82:85], v[172:175], v[200:203], v[82:85]
	v_mfma_f32_16x16x32_bf16 v[74:77], v[176:179], v[200:203], v[74:77]
	v_mfma_f32_16x16x32_bf16 v[70:73], v[172:175], v[208:211], v[70:73]
	v_mfma_f32_16x16x32_bf16 v[66:69], v[176:179], v[208:211], v[66:69]
	s_setprio 0
	s_barrier
	s_add_i32 s2, s0, s15
	s_mov_b32 m0, s2
	ds_read_b128 v[180:183], v145 offset:16384
	ds_read_b128 v[184:187], v145 offset:17408
	ds_read_b128 v[188:191], v145 offset:18432
	ds_read_b128 v[192:195], v145 offset:19456
	global_load_lds_dwordx4 v132, s[92:93]
	s_add_i32 m0, s2, 0x2000
	s_add_i32 s2, s1, s15
	global_load_lds_dwordx4 v136, s[92:93]
	s_mov_b32 m0, s2
	ds_read_b128 v[196:199], v145 offset:20480
	global_load_lds_dwordx4 v132, s[98:99]
	s_add_i32 m0, s2, 0x2000
	ds_read_b128 v[200:203], v145 offset:21504
	global_load_lds_dwordx4 v136, s[98:99]
	s_mov_b32 m0, s68
	ds_read_b128 v[204:207], v145 offset:22528
	global_load_lds_dwordx4 v130, s[4:5]
	s_mov_b32 m0, s69
	ds_read_b128 v[208:211], v145 offset:23552
	global_load_lds_dwordx4 v134, s[4:5]
	s_waitcnt vmcnt(8)
	s_waitcnt lgkmcnt(0)
	s_barrier
	s_setprio 1
	s_waitcnt lgkmcnt(0)
	v_mfma_f32_16x16x32_bf16 v[62:65], v[148:151], v[180:183], v[62:65]
	v_mfma_f32_16x16x32_bf16 v[58:61], v[152:155], v[180:183], v[58:61]
	v_mfma_f32_16x16x32_bf16 v[54:57], v[148:151], v[188:191], v[54:57]
	v_mfma_f32_16x16x32_bf16 v[46:49], v[152:155], v[188:191], v[46:49]
	v_mfma_f32_16x16x32_bf16 v[38:41], v[148:151], v[196:199], v[38:41]
	v_mfma_f32_16x16x32_bf16 v[30:33], v[152:155], v[196:199], v[30:33]
	v_mfma_f32_16x16x32_bf16 v[22:25], v[148:151], v[204:207], v[22:25]
	v_mfma_f32_16x16x32_bf16 v[14:17], v[152:155], v[204:207], v[14:17]
	v_mfma_f32_16x16x32_bf16 v[62:65], v[156:159], v[184:187], v[62:65]
	v_mfma_f32_16x16x32_bf16 v[58:61], v[160:163], v[184:187], v[58:61]
	v_mfma_f32_16x16x32_bf16 v[54:57], v[156:159], v[192:195], v[54:57]
	v_mfma_f32_16x16x32_bf16 v[46:49], v[160:163], v[192:195], v[46:49]
	v_mfma_f32_16x16x32_bf16 v[38:41], v[156:159], v[200:203], v[38:41]
	v_mfma_f32_16x16x32_bf16 v[30:33], v[160:163], v[200:203], v[30:33]
	v_mfma_f32_16x16x32_bf16 v[22:25], v[156:159], v[208:211], v[22:25]
	v_mfma_f32_16x16x32_bf16 v[14:17], v[160:163], v[208:211], v[14:17]
	s_setprio 0
	s_setprio 1
	v_mfma_f32_16x16x32_bf16 v[50:53], v[164:167], v[180:183], v[50:53]
	v_mfma_f32_16x16x32_bf16 v[42:45], v[168:171], v[180:183], v[42:45]
	v_mfma_f32_16x16x32_bf16 v[34:37], v[164:167], v[188:191], v[34:37]
	v_mfma_f32_16x16x32_bf16 v[26:29], v[168:171], v[188:191], v[26:29]
	v_mfma_f32_16x16x32_bf16 v[18:21], v[164:167], v[196:199], v[18:21]
	v_mfma_f32_16x16x32_bf16 v[10:13], v[168:171], v[196:199], v[10:13]
	v_mfma_f32_16x16x32_bf16 v[6:9], v[164:167], v[204:207], v[6:9]
	v_mfma_f32_16x16x32_bf16 v[2:5], v[168:171], v[204:207], v[2:5]
	v_mfma_f32_16x16x32_bf16 v[50:53], v[172:175], v[184:187], v[50:53]
	v_mfma_f32_16x16x32_bf16 v[42:45], v[176:179], v[184:187], v[42:45]
	v_mfma_f32_16x16x32_bf16 v[34:37], v[172:175], v[192:195], v[34:37]
	v_mfma_f32_16x16x32_bf16 v[26:29], v[176:179], v[192:195], v[26:29]
	v_mfma_f32_16x16x32_bf16 v[18:21], v[172:175], v[200:203], v[18:21]
	v_mfma_f32_16x16x32_bf16 v[10:13], v[176:179], v[200:203], v[10:13]
	v_mfma_f32_16x16x32_bf16 v[6:9], v[172:175], v[208:211], v[6:9]
	v_mfma_f32_16x16x32_bf16 v[2:5], v[176:179], v[208:211], v[2:5]
	s_setprio 0
	s_barrier
	s_add_i32 s12, 0, 0x18000
	v_add_u32_e32 v147, s12, v1
	s_add_i32 s13, 0, 0x1c000
	ds_read_b128 v[148:151], v147
	ds_read_b128 v[152:155], v147 offset:256
	ds_read_b128 v[156:159], v147 offset:8192
	ds_read_b128 v[160:163], v147 offset:8448
	v_add_u32_e32 v147, s13, v1
	ds_read_b128 v[164:167], v147
	ds_read_b128 v[168:171], v147 offset:256
	ds_read_b128 v[172:175], v147 offset:8192
	ds_read_b128 v[176:179], v147 offset:8448
	s_add_u32 s2, s4, 0x104000
	s_addc_u32 s3, s5, 0
	s_mov_b32 m0, s70
	ds_read_b128 v[180:183], v145 offset:32768
	ds_read_b128 v[184:187], v145 offset:33792
	ds_read_b128 v[188:191], v145 offset:34816
	ds_read_b128 v[192:195], v145 offset:35840
	ds_read_b128 v[196:199], v145 offset:36864
	ds_read_b128 v[200:203], v145 offset:37888
	ds_read_b128 v[204:207], v145 offset:38912
	global_load_lds_dwordx4 v130, s[2:3]
	s_mov_b32 m0, s71
	ds_read_b128 v[208:211], v145 offset:39936
	global_load_lds_dwordx4 v134, s[2:3]
	s_waitcnt vmcnt(8)
	s_waitcnt lgkmcnt(0)
	s_barrier
	s_setprio 1
	s_waitcnt lgkmcnt(0)
	v_mfma_f32_16x16x32_bf16 v[126:129], v[148:151], v[180:183], v[126:129]
	v_mfma_f32_16x16x32_bf16 v[122:125], v[152:155], v[180:183], v[122:125]
	v_mfma_f32_16x16x32_bf16 v[118:121], v[148:151], v[188:191], v[118:121]
	v_mfma_f32_16x16x32_bf16 v[110:113], v[152:155], v[188:191], v[110:113]
	v_mfma_f32_16x16x32_bf16 v[102:105], v[148:151], v[196:199], v[102:105]
	v_mfma_f32_16x16x32_bf16 v[94:97], v[152:155], v[196:199], v[94:97]
	v_mfma_f32_16x16x32_bf16 v[86:89], v[148:151], v[204:207], v[86:89]
	v_mfma_f32_16x16x32_bf16 v[78:81], v[152:155], v[204:207], v[78:81]
	v_mfma_f32_16x16x32_bf16 v[126:129], v[156:159], v[184:187], v[126:129]
	v_mfma_f32_16x16x32_bf16 v[122:125], v[160:163], v[184:187], v[122:125]
	v_mfma_f32_16x16x32_bf16 v[118:121], v[156:159], v[192:195], v[118:121]
	v_mfma_f32_16x16x32_bf16 v[110:113], v[160:163], v[192:195], v[110:113]
	v_mfma_f32_16x16x32_bf16 v[102:105], v[156:159], v[200:203], v[102:105]
	v_mfma_f32_16x16x32_bf16 v[94:97], v[160:163], v[200:203], v[94:97]
	v_mfma_f32_16x16x32_bf16 v[86:89], v[156:159], v[208:211], v[86:89]
	v_mfma_f32_16x16x32_bf16 v[78:81], v[160:163], v[208:211], v[78:81]
	s_setprio 0
	s_setprio 1
	v_mfma_f32_16x16x32_bf16 v[114:117], v[164:167], v[180:183], v[114:117]
	v_mfma_f32_16x16x32_bf16 v[106:109], v[168:171], v[180:183], v[106:109]
	v_mfma_f32_16x16x32_bf16 v[98:101], v[164:167], v[188:191], v[98:101]
	v_mfma_f32_16x16x32_bf16 v[90:93], v[168:171], v[188:191], v[90:93]
	v_mfma_f32_16x16x32_bf16 v[82:85], v[164:167], v[196:199], v[82:85]
	v_mfma_f32_16x16x32_bf16 v[74:77], v[168:171], v[196:199], v[74:77]
	v_mfma_f32_16x16x32_bf16 v[70:73], v[164:167], v[204:207], v[70:73]
	v_mfma_f32_16x16x32_bf16 v[66:69], v[168:171], v[204:207], v[66:69]
	v_mfma_f32_16x16x32_bf16 v[114:117], v[172:175], v[184:187], v[114:117]
	v_mfma_f32_16x16x32_bf16 v[106:109], v[176:179], v[184:187], v[106:109]
	v_mfma_f32_16x16x32_bf16 v[98:101], v[172:175], v[192:195], v[98:101]
	v_mfma_f32_16x16x32_bf16 v[90:93], v[176:179], v[192:195], v[90:93]
	v_mfma_f32_16x16x32_bf16 v[82:85], v[172:175], v[200:203], v[82:85]
	v_mfma_f32_16x16x32_bf16 v[74:77], v[176:179], v[200:203], v[74:77]
	v_mfma_f32_16x16x32_bf16 v[70:73], v[172:175], v[208:211], v[70:73]
	v_mfma_f32_16x16x32_bf16 v[66:69], v[176:179], v[208:211], v[66:69]
	s_setprio 0
	s_barrier
	s_add_i32 s2, s12, s15
	s_mov_b32 m0, s2
	ds_read_b128 v[180:183], v145 offset:49152
	ds_read_b128 v[184:187], v145 offset:50176
	ds_read_b128 v[188:191], v145 offset:51200
	ds_read_b128 v[192:195], v145 offset:52224
	global_load_lds_dwordx4 v132, s[94:95]
	s_add_i32 m0, s2, 0x2000
	s_add_u32 s2, s92, 0x189000
	s_addc_u32 s3, s93, 0
	s_add_i32 s4, s13, s15
	global_load_lds_dwordx4 v136, s[94:95]
	s_mov_b32 m0, s4
	ds_read_b128 v[196:199], v145 offset:53248
	global_load_lds_dwordx4 v132, s[2:3]
	s_add_i32 m0, s4, 0x2000
	ds_read_b128 v[200:203], v145 offset:54272
	global_load_lds_dwordx4 v136, s[2:3]
	s_mov_b32 m0, s8
	ds_read_b128 v[204:207], v145 offset:55296
	global_load_lds_dwordx4 v130, s[100:101]
	s_mov_b32 m0, s9
	ds_read_b128 v[208:211], v145 offset:56320
	global_load_lds_dwordx4 v134, s[100:101]
	s_waitcnt vmcnt(8)
	s_waitcnt lgkmcnt(0)
	s_barrier
	s_setprio 1
	s_waitcnt lgkmcnt(0)
	v_mfma_f32_16x16x32_bf16 v[62:65], v[148:151], v[180:183], v[62:65]
	v_mfma_f32_16x16x32_bf16 v[58:61], v[152:155], v[180:183], v[58:61]
	v_mfma_f32_16x16x32_bf16 v[54:57], v[148:151], v[188:191], v[54:57]
	v_mfma_f32_16x16x32_bf16 v[46:49], v[152:155], v[188:191], v[46:49]
	v_mfma_f32_16x16x32_bf16 v[38:41], v[148:151], v[196:199], v[38:41]
	v_mfma_f32_16x16x32_bf16 v[30:33], v[152:155], v[196:199], v[30:33]
	v_mfma_f32_16x16x32_bf16 v[22:25], v[148:151], v[204:207], v[22:25]
	v_mfma_f32_16x16x32_bf16 v[14:17], v[152:155], v[204:207], v[14:17]
	v_mfma_f32_16x16x32_bf16 v[62:65], v[156:159], v[184:187], v[62:65]
	v_mfma_f32_16x16x32_bf16 v[58:61], v[160:163], v[184:187], v[58:61]
	v_mfma_f32_16x16x32_bf16 v[54:57], v[156:159], v[192:195], v[54:57]
	v_mfma_f32_16x16x32_bf16 v[46:49], v[160:163], v[192:195], v[46:49]
	v_mfma_f32_16x16x32_bf16 v[38:41], v[156:159], v[200:203], v[38:41]
	v_mfma_f32_16x16x32_bf16 v[30:33], v[160:163], v[200:203], v[30:33]
	v_mfma_f32_16x16x32_bf16 v[22:25], v[156:159], v[208:211], v[22:25]
	v_mfma_f32_16x16x32_bf16 v[14:17], v[160:163], v[208:211], v[14:17]
	s_setprio 0
	s_setprio 1
	v_mfma_f32_16x16x32_bf16 v[50:53], v[164:167], v[180:183], v[50:53]
	v_mfma_f32_16x16x32_bf16 v[42:45], v[168:171], v[180:183], v[42:45]
	v_mfma_f32_16x16x32_bf16 v[34:37], v[164:167], v[188:191], v[34:37]
	v_mfma_f32_16x16x32_bf16 v[26:29], v[168:171], v[188:191], v[26:29]
	v_mfma_f32_16x16x32_bf16 v[18:21], v[164:167], v[196:199], v[18:21]
	v_mfma_f32_16x16x32_bf16 v[10:13], v[168:171], v[196:199], v[10:13]
	v_mfma_f32_16x16x32_bf16 v[6:9], v[164:167], v[204:207], v[6:9]
	v_mfma_f32_16x16x32_bf16 v[2:5], v[168:171], v[204:207], v[2:5]
	v_mfma_f32_16x16x32_bf16 v[50:53], v[172:175], v[184:187], v[50:53]
	v_mfma_f32_16x16x32_bf16 v[42:45], v[176:179], v[184:187], v[42:45]
	v_mfma_f32_16x16x32_bf16 v[34:37], v[172:175], v[192:195], v[34:37]
	v_mfma_f32_16x16x32_bf16 v[26:29], v[176:179], v[192:195], v[26:29]
	v_mfma_f32_16x16x32_bf16 v[18:21], v[172:175], v[200:203], v[18:21]
	v_mfma_f32_16x16x32_bf16 v[10:13], v[176:179], v[200:203], v[10:13]
	v_mfma_f32_16x16x32_bf16 v[6:9], v[172:175], v[208:211], v[6:9]
	v_mfma_f32_16x16x32_bf16 v[2:5], v[176:179], v[208:211], v[2:5]
	s_setprio 0
	s_barrier
	s_add_i32 s2, s87, 2
	s_cmp_gt_u32 s87, 61
	s_cbranch_scc1 .LBB0_255
	s_mov_b32 s87, s2
	s_branch .LBB0_220

.LBB0_558:
	s_lshl_b32 s2, s69, 7
	s_add_u32 s20, s74, s2
	s_addc_u32 s21, s75, 0
	s_add_u32 s4, s20, 0x100
	s_addc_u32 s5, s21, 0
	s_and_b64 s[2:3], s[82:83], exec
	s_mul_i32 s2, s69, 0x88800
	v_add_u32_e32 v188, s93, v1
	v_add_u32_e32 v204, s18, v1
	s_cselect_b32 s5, s5, s63
	s_cselect_b32 s4, s4, s62
	s_add_u32 s2, s78, s2
	ds_read_b128 v[130:133], v188
	ds_read_b128 v[134:137], v188 offset:256
	ds_read_b128 v[180:183], v188 offset:8192
	ds_read_b128 v[188:191], v188 offset:8448
	ds_read_b128 v[192:195], v204
	ds_read_b128 v[196:199], v204 offset:256
	ds_read_b128 v[200:203], v204 offset:8192
	ds_read_b128 v[204:207], v204 offset:8448
	s_addc_u32 s3, s79, 0
	s_add_u32 s22, s2, 0x111000
	s_addc_u32 s23, s3, 0
	s_and_b64 s[2:3], s[82:83], exec
	s_cselect_b32 s82, s22, s61
	s_cselect_b32 s83, s23, s14
	s_add_u32 s84, s82, 0x88800
	s_addc_u32 s85, s83, 0
	s_add_u32 s98, s82, s12
	s_addc_u32 s99, s83, s13
	s_add_u32 s100, s4, s56
	s_addc_u32 s101, s5, s57
	s_add_u32 s2, s20, 0x104080
	s_addc_u32 s3, s21, 0
	s_add_i32 m0, s94, 0xc000
	ds_read_b128 v[208:211], v186
	ds_read_b128 v[212:215], v186 offset:1024
	ds_read_b128 v[216:219], v186 offset:2048
	ds_read_b128 v[220:223], v186 offset:3072
	ds_read_b128 v[224:227], v186 offset:4096
	ds_read_b128 v[228:231], v186 offset:5120
	ds_read_b128 v[232:235], v186 offset:6144
	global_load_lds_dwordx4 v138, s[2:3]
	s_add_i32 m0, s94, 0xe000
	ds_read_b128 v[236:239], v186 offset:7168
	global_load_lds_dwordx4 v142, s[2:3]
	s_waitcnt vmcnt(8)
	s_waitcnt lgkmcnt(0)
	s_barrier
	s_setprio 1
	s_waitcnt lgkmcnt(0)
	v_mfma_f32_16x16x32_bf16 v[126:129], v[130:133], v[208:211], v[126:129]
	v_mfma_f32_16x16x32_bf16 v[122:125], v[134:137], v[208:211], v[122:125]
	v_mfma_f32_16x16x32_bf16 v[110:113], v[130:133], v[216:219], v[110:113]
	v_mfma_f32_16x16x32_bf16 v[106:109], v[134:137], v[216:219], v[106:109]
	v_mfma_f32_16x16x32_bf16 v[94:97], v[130:133], v[224:227], v[94:97]
	v_mfma_f32_16x16x32_bf16 v[90:93], v[134:137], v[224:227], v[90:93]
	v_mfma_f32_16x16x32_bf16 v[78:81], v[130:133], v[232:235], v[78:81]
	v_mfma_f32_16x16x32_bf16 v[74:77], v[134:137], v[232:235], v[74:77]
	v_mfma_f32_16x16x32_bf16 v[126:129], v[180:183], v[212:215], v[126:129]
	v_mfma_f32_16x16x32_bf16 v[122:125], v[188:191], v[212:215], v[122:125]
	v_mfma_f32_16x16x32_bf16 v[110:113], v[180:183], v[220:223], v[110:113]
	v_mfma_f32_16x16x32_bf16 v[106:109], v[188:191], v[220:223], v[106:109]
	v_mfma_f32_16x16x32_bf16 v[94:97], v[180:183], v[228:231], v[94:97]
	v_mfma_f32_16x16x32_bf16 v[90:93], v[188:191], v[228:231], v[90:93]
	v_mfma_f32_16x16x32_bf16 v[78:81], v[180:183], v[236:239], v[78:81]
	v_mfma_f32_16x16x32_bf16 v[74:77], v[188:191], v[236:239], v[74:77]
	s_setprio 0
	s_setprio 1
	v_mfma_f32_16x16x32_bf16 v[118:121], v[192:195], v[208:211], v[118:121]
	v_mfma_f32_16x16x32_bf16 v[114:117], v[196:199], v[208:211], v[114:117]
	v_mfma_f32_16x16x32_bf16 v[102:105], v[192:195], v[216:219], v[102:105]
	v_mfma_f32_16x16x32_bf16 v[98:101], v[196:199], v[216:219], v[98:101]
	v_mfma_f32_16x16x32_bf16 v[86:89], v[192:195], v[224:227], v[86:89]
	v_mfma_f32_16x16x32_bf16 v[82:85], v[196:199], v[224:227], v[82:85]
	v_mfma_f32_16x16x32_bf16 v[70:73], v[192:195], v[232:235], v[70:73]
	v_mfma_f32_16x16x32_bf16 v[66:69], v[196:199], v[232:235], v[66:69]
	v_mfma_f32_16x16x32_bf16 v[118:121], v[200:203], v[212:215], v[118:121]
	v_mfma_f32_16x16x32_bf16 v[114:117], v[204:207], v[212:215], v[114:117]
	v_mfma_f32_16x16x32_bf16 v[102:105], v[200:203], v[220:223], v[102:105]
	v_mfma_f32_16x16x32_bf16 v[98:101], v[204:207], v[220:223], v[98:101]
	v_mfma_f32_16x16x32_bf16 v[86:89], v[200:203], v[228:231], v[86:89]
	v_mfma_f32_16x16x32_bf16 v[82:85], v[204:207], v[228:231], v[82:85]
	v_mfma_f32_16x16x32_bf16 v[70:73], v[200:203], v[236:239], v[70:73]
	v_mfma_f32_16x16x32_bf16 v[66:69], v[204:207], v[236:239], v[66:69]
	s_setprio 0
	s_barrier
	s_add_i32 s2, s93, s73
	s_mov_b32 m0, s2
	ds_read_b128 v[208:211], v186 offset:16384
	ds_read_b128 v[212:215], v186 offset:17408
	ds_read_b128 v[216:219], v186 offset:18432
	ds_read_b128 v[220:223], v186 offset:19456
	global_load_lds_dwordx4 v140, s[82:83]
	s_add_i32 m0, s2, 0x2000
	s_add_i32 s2, s18, s73
	global_load_lds_dwordx4 v144, s[82:83]
	s_mov_b32 m0, s2
	ds_read_b128 v[224:227], v186 offset:20480
	global_load_lds_dwordx4 v140, s[98:99]
	s_add_i32 m0, s2, 0x2000
	ds_read_b128 v[228:231], v186 offset:21504
	global_load_lds_dwordx4 v144, s[98:99]
	s_mov_b32 m0, s94
	ds_read_b128 v[232:235], v186 offset:22528
	global_load_lds_dwordx4 v138, s[4:5]
	s_mov_b32 m0, s95
	ds_read_b128 v[236:239], v186 offset:23552
	global_load_lds_dwordx4 v142, s[4:5]
	s_waitcnt vmcnt(8)
	s_waitcnt lgkmcnt(0)
	s_barrier
	s_setprio 1
	s_waitcnt lgkmcnt(0)
	v_mfma_f32_16x16x32_bf16 v[62:65], v[130:133], v[208:211], v[62:65]
	v_mfma_f32_16x16x32_bf16 v[58:61], v[134:137], v[208:211], v[58:61]
	v_mfma_f32_16x16x32_bf16 v[46:49], v[130:133], v[216:219], v[46:49]
	v_mfma_f32_16x16x32_bf16 v[42:45], v[134:137], v[216:219], v[42:45]
	v_mfma_f32_16x16x32_bf16 v[30:33], v[130:133], v[224:227], v[30:33]
	v_mfma_f32_16x16x32_bf16 v[26:29], v[134:137], v[224:227], v[26:29]
	v_mfma_f32_16x16x32_bf16 v[14:17], v[130:133], v[232:235], v[14:17]
	v_mfma_f32_16x16x32_bf16 v[10:13], v[134:137], v[232:235], v[10:13]
	v_mfma_f32_16x16x32_bf16 v[62:65], v[180:183], v[212:215], v[62:65]
	v_mfma_f32_16x16x32_bf16 v[58:61], v[188:191], v[212:215], v[58:61]
	v_mfma_f32_16x16x32_bf16 v[46:49], v[180:183], v[220:223], v[46:49]
	v_mfma_f32_16x16x32_bf16 v[42:45], v[188:191], v[220:223], v[42:45]
	v_mfma_f32_16x16x32_bf16 v[30:33], v[180:183], v[228:231], v[30:33]
	v_mfma_f32_16x16x32_bf16 v[26:29], v[188:191], v[228:231], v[26:29]
	v_mfma_f32_16x16x32_bf16 v[14:17], v[180:183], v[236:239], v[14:17]
	v_mfma_f32_16x16x32_bf16 v[10:13], v[188:191], v[236:239], v[10:13]
	s_setprio 0
	s_setprio 1
	v_mfma_f32_16x16x32_bf16 v[54:57], v[192:195], v[208:211], v[54:57]
	v_mfma_f32_16x16x32_bf16 v[50:53], v[196:199], v[208:211], v[50:53]
	v_mfma_f32_16x16x32_bf16 v[38:41], v[192:195], v[216:219], v[38:41]
	v_mfma_f32_16x16x32_bf16 v[34:37], v[196:199], v[216:219], v[34:37]
	v_mfma_f32_16x16x32_bf16 v[22:25], v[192:195], v[224:227], v[22:25]
	v_mfma_f32_16x16x32_bf16 v[18:21], v[196:199], v[224:227], v[18:21]
	v_mfma_f32_16x16x32_bf16 v[6:9], v[192:195], v[232:235], v[6:9]
	v_mfma_f32_16x16x32_bf16 v[2:5], v[196:199], v[232:235], v[2:5]
	v_mfma_f32_16x16x32_bf16 v[54:57], v[200:203], v[212:215], v[54:57]
	v_mfma_f32_16x16x32_bf16 v[50:53], v[204:207], v[212:215], v[50:53]
	v_mfma_f32_16x16x32_bf16 v[38:41], v[200:203], v[220:223], v[38:41]
	v_mfma_f32_16x16x32_bf16 v[34:37], v[204:207], v[220:223], v[34:37]
	v_mfma_f32_16x16x32_bf16 v[22:25], v[200:203], v[228:231], v[22:25]
	v_mfma_f32_16x16x32_bf16 v[18:21], v[204:207], v[228:231], v[18:21]
	v_mfma_f32_16x16x32_bf16 v[6:9], v[200:203], v[236:239], v[6:9]
	v_mfma_f32_16x16x32_bf16 v[2:5], v[204:207], v[236:239], v[2:5]
	s_setprio 0
	s_barrier
	s_add_i32 s20, 0, 0x18000
	s_add_i32 s21, 0, 0x1c000
	v_add_u32_e32 v188, s20, v1
	v_add_u32_e32 v204, s21, v1
	ds_read_b128 v[130:133], v188
	ds_read_b128 v[134:137], v188 offset:256
	ds_read_b128 v[180:183], v188 offset:8192
	ds_read_b128 v[188:191], v188 offset:8448
	ds_read_b128 v[192:195], v204
	ds_read_b128 v[196:199], v204 offset:256
	ds_read_b128 v[200:203], v204 offset:8192
	ds_read_b128 v[204:207], v204 offset:8448
	s_add_u32 s2, s4, 0x104000
	s_addc_u32 s3, s5, 0
	s_mov_b32 m0, s96
	ds_read_b128 v[208:211], v186 offset:32768
	ds_read_b128 v[212:215], v186 offset:33792
	ds_read_b128 v[216:219], v186 offset:34816
	ds_read_b128 v[220:223], v186 offset:35840
	ds_read_b128 v[224:227], v186 offset:36864
	ds_read_b128 v[228:231], v186 offset:37888
	ds_read_b128 v[232:235], v186 offset:38912
	global_load_lds_dwordx4 v138, s[2:3]
	s_mov_b32 m0, s97
	ds_read_b128 v[236:239], v186 offset:39936
	global_load_lds_dwordx4 v142, s[2:3]
	s_waitcnt vmcnt(8)
	s_waitcnt lgkmcnt(0)
	s_barrier
	s_setprio 1
	s_waitcnt lgkmcnt(0)
	v_mfma_f32_16x16x32_bf16 v[126:129], v[130:133], v[208:211], v[126:129]
	v_mfma_f32_16x16x32_bf16 v[122:125], v[134:137], v[208:211], v[122:125]
	v_mfma_f32_16x16x32_bf16 v[110:113], v[130:133], v[216:219], v[110:113]
	v_mfma_f32_16x16x32_bf16 v[106:109], v[134:137], v[216:219], v[106:109]
	v_mfma_f32_16x16x32_bf16 v[94:97], v[130:133], v[224:227], v[94:97]
	v_mfma_f32_16x16x32_bf16 v[90:93], v[134:137], v[224:227], v[90:93]
	v_mfma_f32_16x16x32_bf16 v[78:81], v[130:133], v[232:235], v[78:81]
	v_mfma_f32_16x16x32_bf16 v[74:77], v[134:137], v[232:235], v[74:77]
	v_mfma_f32_16x16x32_bf16 v[126:129], v[180:183], v[212:215], v[126:129]
	v_mfma_f32_16x16x32_bf16 v[122:125], v[188:191], v[212:215], v[122:125]
	v_mfma_f32_16x16x32_bf16 v[110:113], v[180:183], v[220:223], v[110:113]
	v_mfma_f32_16x16x32_bf16 v[106:109], v[188:191], v[220:223], v[106:109]
	v_mfma_f32_16x16x32_bf16 v[94:97], v[180:183], v[228:231], v[94:97]
	v_mfma_f32_16x16x32_bf16 v[90:93], v[188:191], v[228:231], v[90:93]
	v_mfma_f32_16x16x32_bf16 v[78:81], v[180:183], v[236:239], v[78:81]
	v_mfma_f32_16x16x32_bf16 v[74:77], v[188:191], v[236:239], v[74:77]
	s_setprio 0
	s_setprio 1
	v_mfma_f32_16x16x32_bf16 v[118:121], v[192:195], v[208:211], v[118:121]
	v_mfma_f32_16x16x32_bf16 v[114:117], v[196:199], v[208:211], v[114:117]
	v_mfma_f32_16x16x32_bf16 v[102:105], v[192:195], v[216:219], v[102:105]
	v_mfma_f32_16x16x32_bf16 v[98:101], v[196:199], v[216:219], v[98:101]
	v_mfma_f32_16x16x32_bf16 v[86:89], v[192:195], v[224:227], v[86:89]
	v_mfma_f32_16x16x32_bf16 v[82:85], v[196:199], v[224:227], v[82:85]
	v_mfma_f32_16x16x32_bf16 v[70:73], v[192:195], v[232:235], v[70:73]
	v_mfma_f32_16x16x32_bf16 v[66:69], v[196:199], v[232:235], v[66:69]
	v_mfma_f32_16x16x32_bf16 v[118:121], v[200:203], v[212:215], v[118:121]
	v_mfma_f32_16x16x32_bf16 v[114:117], v[204:207], v[212:215], v[114:117]
	v_mfma_f32_16x16x32_bf16 v[102:105], v[200:203], v[220:223], v[102:105]
	v_mfma_f32_16x16x32_bf16 v[98:101], v[204:207], v[220:223], v[98:101]
	v_mfma_f32_16x16x32_bf16 v[86:89], v[200:203], v[228:231], v[86:89]
	v_mfma_f32_16x16x32_bf16 v[82:85], v[204:207], v[228:231], v[82:85]
	v_mfma_f32_16x16x32_bf16 v[70:73], v[200:203], v[236:239], v[70:73]
	v_mfma_f32_16x16x32_bf16 v[66:69], v[204:207], v[236:239], v[66:69]
	s_setprio 0
	s_barrier
	s_add_i32 s2, s20, s73
	s_mov_b32 m0, s2
	ds_read_b128 v[208:211], v186 offset:49152
	ds_read_b128 v[212:215], v186 offset:50176
	ds_read_b128 v[216:219], v186 offset:51200
	ds_read_b128 v[220:223], v186 offset:52224
	global_load_lds_dwordx4 v140, s[84:85]
	s_add_i32 m0, s2, 0x2000
	s_add_u32 s2, s82, 0x89000
	s_addc_u32 s3, s83, 0
	s_add_i32 s4, s21, s73
	global_load_lds_dwordx4 v144, s[84:85]
	s_mov_b32 m0, s4
	ds_read_b128 v[224:227], v186 offset:53248
	global_load_lds_dwordx4 v140, s[2:3]
	s_add_i32 m0, s4, 0x2000
	ds_read_b128 v[228:231], v186 offset:54272
	global_load_lds_dwordx4 v144, s[2:3]
	s_mov_b32 m0, s53
	ds_read_b128 v[232:235], v186 offset:55296
	global_load_lds_dwordx4 v138, s[100:101]
	s_mov_b32 m0, s92
	ds_read_b128 v[236:239], v186 offset:56320
	global_load_lds_dwordx4 v142, s[100:101]
	s_waitcnt vmcnt(8)
	s_waitcnt lgkmcnt(0)
	s_barrier
	s_setprio 1
	s_waitcnt lgkmcnt(0)
	v_mfma_f32_16x16x32_bf16 v[62:65], v[130:133], v[208:211], v[62:65]
	v_mfma_f32_16x16x32_bf16 v[58:61], v[134:137], v[208:211], v[58:61]
	v_mfma_f32_16x16x32_bf16 v[46:49], v[130:133], v[216:219], v[46:49]
	v_mfma_f32_16x16x32_bf16 v[42:45], v[134:137], v[216:219], v[42:45]
	v_mfma_f32_16x16x32_bf16 v[30:33], v[130:133], v[224:227], v[30:33]
	v_mfma_f32_16x16x32_bf16 v[26:29], v[134:137], v[224:227], v[26:29]
	v_mfma_f32_16x16x32_bf16 v[14:17], v[130:133], v[232:235], v[14:17]
	v_mfma_f32_16x16x32_bf16 v[10:13], v[134:137], v[232:235], v[10:13]
	v_mfma_f32_16x16x32_bf16 v[62:65], v[180:183], v[212:215], v[62:65]
	v_mfma_f32_16x16x32_bf16 v[58:61], v[188:191], v[212:215], v[58:61]
	v_mfma_f32_16x16x32_bf16 v[46:49], v[180:183], v[220:223], v[46:49]
	v_mfma_f32_16x16x32_bf16 v[42:45], v[188:191], v[220:223], v[42:45]
	v_mfma_f32_16x16x32_bf16 v[30:33], v[180:183], v[228:231], v[30:33]
	v_mfma_f32_16x16x32_bf16 v[26:29], v[188:191], v[228:231], v[26:29]
	v_mfma_f32_16x16x32_bf16 v[14:17], v[180:183], v[236:239], v[14:17]
	v_mfma_f32_16x16x32_bf16 v[10:13], v[188:191], v[236:239], v[10:13]
	s_setprio 0
	s_setprio 1
	v_mfma_f32_16x16x32_bf16 v[54:57], v[192:195], v[208:211], v[54:57]
	v_mfma_f32_16x16x32_bf16 v[50:53], v[196:199], v[208:211], v[50:53]
	v_mfma_f32_16x16x32_bf16 v[38:41], v[192:195], v[216:219], v[38:41]
	v_mfma_f32_16x16x32_bf16 v[34:37], v[196:199], v[216:219], v[34:37]
	v_mfma_f32_16x16x32_bf16 v[22:25], v[192:195], v[224:227], v[22:25]
	v_mfma_f32_16x16x32_bf16 v[18:21], v[196:199], v[224:227], v[18:21]
	v_mfma_f32_16x16x32_bf16 v[6:9], v[192:195], v[232:235], v[6:9]
	v_mfma_f32_16x16x32_bf16 v[2:5], v[196:199], v[232:235], v[2:5]
	v_mfma_f32_16x16x32_bf16 v[54:57], v[200:203], v[212:215], v[54:57]
	v_mfma_f32_16x16x32_bf16 v[50:53], v[204:207], v[212:215], v[50:53]
	v_mfma_f32_16x16x32_bf16 v[38:41], v[200:203], v[220:223], v[38:41]
	v_mfma_f32_16x16x32_bf16 v[34:37], v[204:207], v[220:223], v[34:37]
	v_mfma_f32_16x16x32_bf16 v[22:25], v[200:203], v[228:231], v[22:25]
	v_mfma_f32_16x16x32_bf16 v[18:21], v[204:207], v[228:231], v[18:21]
	v_mfma_f32_16x16x32_bf16 v[6:9], v[200:203], v[236:239], v[6:9]
	v_mfma_f32_16x16x32_bf16 v[2:5], v[204:207], v[236:239], v[2:5]
	s_setprio 0
	s_barrier
	s_add_i32 s2, s69, 2
	s_cmp_gt_u32 s69, 61
	s_cbranch_scc1 .LBB0_564
	s_mov_b32 s69, s2
	s_branch .LBB0_529

.LBB0_796:
	s_lshl_b32 s2, s90, 7
	s_add_u32 s20, s54, s2
	s_addc_u32 s21, s55, 0
	s_add_u32 s4, s20, 0x100
	s_addc_u32 s5, s21, 0
	s_and_b64 s[2:3], s[60:61], exec
	v_add_u32_e32 v140, s83, v1
	s_mul_i32 s2, s90, 0x208800
	ds_read_b128 v[148:151], v140
	ds_read_b128 v[152:155], v140 offset:256
	ds_read_b128 v[156:159], v140 offset:8192
	ds_read_b128 v[160:163], v140 offset:8448
	v_add_u32_e32 v140, s84, v1
	s_cselect_b32 s5, s5, s43
	s_cselect_b32 s4, s4, s42
	s_add_u32 s2, s56, s2
	ds_read_b128 v[164:167], v140
	ds_read_b128 v[168:171], v140 offset:256
	ds_read_b128 v[172:175], v140 offset:8192
	ds_read_b128 v[176:179], v140 offset:8448
	s_addc_u32 s3, s57, 0
	s_add_u32 s22, s2, 0x411000
	s_addc_u32 s23, s3, 0
	s_and_b64 s[2:3], s[60:61], exec
	s_cselect_b32 s60, s22, s89
	s_cselect_b32 s61, s23, s35
	s_add_u32 s62, s60, 0x208800
	s_addc_u32 s63, s61, 0
	s_add_u32 s98, s60, s10
	s_addc_u32 s99, s61, s11
	s_add_u32 s100, s4, s14
	s_addc_u32 s101, s5, s15
	s_add_u32 s2, s20, 0x104080
	s_addc_u32 s3, s21, 0
	s_add_i32 m0, s36, 0xc000
	ds_read_b128 v[180:183], v145
	ds_read_b128 v[184:187], v145 offset:1024
	ds_read_b128 v[188:191], v145 offset:2048
	ds_read_b128 v[192:195], v145 offset:3072
	ds_read_b128 v[196:199], v145 offset:4096
	ds_read_b128 v[200:203], v145 offset:5120
	ds_read_b128 v[204:207], v145 offset:6144
	global_load_lds_dwordx4 v130, s[2:3]
	s_add_i32 m0, s36, 0xe000
	ds_read_b128 v[208:211], v145 offset:7168
	global_load_lds_dwordx4 v134, s[2:3]
	s_waitcnt vmcnt(8)
	s_waitcnt lgkmcnt(0)
	s_barrier
	s_setprio 1
	s_waitcnt lgkmcnt(0)
	v_mfma_f32_16x16x32_bf16 v[126:129], v[148:151], v[180:183], v[126:129]
	v_mfma_f32_16x16x32_bf16 v[122:125], v[152:155], v[180:183], v[122:125]
	v_mfma_f32_16x16x32_bf16 v[110:113], v[148:151], v[188:191], v[110:113]
	v_mfma_f32_16x16x32_bf16 v[106:109], v[152:155], v[188:191], v[106:109]
	v_mfma_f32_16x16x32_bf16 v[94:97], v[148:151], v[196:199], v[94:97]
	v_mfma_f32_16x16x32_bf16 v[90:93], v[152:155], v[196:199], v[90:93]
	v_mfma_f32_16x16x32_bf16 v[78:81], v[148:151], v[204:207], v[78:81]
	v_mfma_f32_16x16x32_bf16 v[74:77], v[152:155], v[204:207], v[74:77]
	v_mfma_f32_16x16x32_bf16 v[126:129], v[156:159], v[184:187], v[126:129]
	v_mfma_f32_16x16x32_bf16 v[122:125], v[160:163], v[184:187], v[122:125]
	v_mfma_f32_16x16x32_bf16 v[110:113], v[156:159], v[192:195], v[110:113]
	v_mfma_f32_16x16x32_bf16 v[106:109], v[160:163], v[192:195], v[106:109]
	v_mfma_f32_16x16x32_bf16 v[94:97], v[156:159], v[200:203], v[94:97]
	v_mfma_f32_16x16x32_bf16 v[90:93], v[160:163], v[200:203], v[90:93]
	v_mfma_f32_16x16x32_bf16 v[78:81], v[156:159], v[208:211], v[78:81]
	v_mfma_f32_16x16x32_bf16 v[74:77], v[160:163], v[208:211], v[74:77]
	s_setprio 0
	s_setprio 1
	v_mfma_f32_16x16x32_bf16 v[118:121], v[164:167], v[180:183], v[118:121]
	v_mfma_f32_16x16x32_bf16 v[114:117], v[168:171], v[180:183], v[114:117]
	v_mfma_f32_16x16x32_bf16 v[102:105], v[164:167], v[188:191], v[102:105]
	v_mfma_f32_16x16x32_bf16 v[98:101], v[168:171], v[188:191], v[98:101]
	v_mfma_f32_16x16x32_bf16 v[86:89], v[164:167], v[196:199], v[86:89]
	v_mfma_f32_16x16x32_bf16 v[82:85], v[168:171], v[196:199], v[82:85]
	v_mfma_f32_16x16x32_bf16 v[70:73], v[164:167], v[204:207], v[70:73]
	v_mfma_f32_16x16x32_bf16 v[66:69], v[168:171], v[204:207], v[66:69]
	v_mfma_f32_16x16x32_bf16 v[118:121], v[172:175], v[184:187], v[118:121]
	v_mfma_f32_16x16x32_bf16 v[114:117], v[176:179], v[184:187], v[114:117]
	v_mfma_f32_16x16x32_bf16 v[102:105], v[172:175], v[192:195], v[102:105]
	v_mfma_f32_16x16x32_bf16 v[98:101], v[176:179], v[192:195], v[98:101]
	v_mfma_f32_16x16x32_bf16 v[86:89], v[172:175], v[200:203], v[86:89]
	v_mfma_f32_16x16x32_bf16 v[82:85], v[176:179], v[200:203], v[82:85]
	v_mfma_f32_16x16x32_bf16 v[70:73], v[172:175], v[208:211], v[70:73]
	v_mfma_f32_16x16x32_bf16 v[66:69], v[176:179], v[208:211], v[66:69]
	s_setprio 0
	s_barrier
	s_add_i32 s2, s83, s18
	s_mov_b32 m0, s2
	ds_read_b128 v[180:183], v145 offset:16384
	ds_read_b128 v[184:187], v145 offset:17408
	ds_read_b128 v[188:191], v145 offset:18432
	ds_read_b128 v[192:195], v145 offset:19456
	global_load_lds_dwordx4 v132, s[60:61]
	s_add_i32 m0, s2, 0x2000
	s_add_i32 s2, s84, s18
	global_load_lds_dwordx4 v136, s[60:61]
	s_mov_b32 m0, s2
	ds_read_b128 v[196:199], v145 offset:20480
	global_load_lds_dwordx4 v132, s[98:99]
	s_add_i32 m0, s2, 0x2000
	ds_read_b128 v[200:203], v145 offset:21504
	global_load_lds_dwordx4 v136, s[98:99]
	s_mov_b32 m0, s36
	ds_read_b128 v[204:207], v145 offset:22528
	global_load_lds_dwordx4 v130, s[4:5]
	s_mov_b32 m0, s37
	ds_read_b128 v[208:211], v145 offset:23552
	global_load_lds_dwordx4 v134, s[4:5]
	s_waitcnt vmcnt(8)
	s_waitcnt lgkmcnt(0)
	s_barrier
	s_setprio 1
	s_waitcnt lgkmcnt(0)
	v_mfma_f32_16x16x32_bf16 v[62:65], v[148:151], v[180:183], v[62:65]
	v_mfma_f32_16x16x32_bf16 v[58:61], v[152:155], v[180:183], v[58:61]
	v_mfma_f32_16x16x32_bf16 v[46:49], v[148:151], v[188:191], v[46:49]
	v_mfma_f32_16x16x32_bf16 v[42:45], v[152:155], v[188:191], v[42:45]
	v_mfma_f32_16x16x32_bf16 v[30:33], v[148:151], v[196:199], v[30:33]
	v_mfma_f32_16x16x32_bf16 v[26:29], v[152:155], v[196:199], v[26:29]
	v_mfma_f32_16x16x32_bf16 v[14:17], v[148:151], v[204:207], v[14:17]
	v_mfma_f32_16x16x32_bf16 v[10:13], v[152:155], v[204:207], v[10:13]
	v_mfma_f32_16x16x32_bf16 v[62:65], v[156:159], v[184:187], v[62:65]
	v_mfma_f32_16x16x32_bf16 v[58:61], v[160:163], v[184:187], v[58:61]
	v_mfma_f32_16x16x32_bf16 v[46:49], v[156:159], v[192:195], v[46:49]
	v_mfma_f32_16x16x32_bf16 v[42:45], v[160:163], v[192:195], v[42:45]
	v_mfma_f32_16x16x32_bf16 v[30:33], v[156:159], v[200:203], v[30:33]
	v_mfma_f32_16x16x32_bf16 v[26:29], v[160:163], v[200:203], v[26:29]
	v_mfma_f32_16x16x32_bf16 v[14:17], v[156:159], v[208:211], v[14:17]
	v_mfma_f32_16x16x32_bf16 v[10:13], v[160:163], v[208:211], v[10:13]
	s_setprio 0
	s_setprio 1
	v_mfma_f32_16x16x32_bf16 v[54:57], v[164:167], v[180:183], v[54:57]
	v_mfma_f32_16x16x32_bf16 v[50:53], v[168:171], v[180:183], v[50:53]
	v_mfma_f32_16x16x32_bf16 v[38:41], v[164:167], v[188:191], v[38:41]
	v_mfma_f32_16x16x32_bf16 v[34:37], v[168:171], v[188:191], v[34:37]
	v_mfma_f32_16x16x32_bf16 v[22:25], v[164:167], v[196:199], v[22:25]
	v_mfma_f32_16x16x32_bf16 v[18:21], v[168:171], v[196:199], v[18:21]
	v_mfma_f32_16x16x32_bf16 v[6:9], v[164:167], v[204:207], v[6:9]
	v_mfma_f32_16x16x32_bf16 v[2:5], v[168:171], v[204:207], v[2:5]
	v_mfma_f32_16x16x32_bf16 v[54:57], v[172:175], v[184:187], v[54:57]
	v_mfma_f32_16x16x32_bf16 v[50:53], v[176:179], v[184:187], v[50:53]
	v_mfma_f32_16x16x32_bf16 v[38:41], v[172:175], v[192:195], v[38:41]
	v_mfma_f32_16x16x32_bf16 v[34:37], v[176:179], v[192:195], v[34:37]
	v_mfma_f32_16x16x32_bf16 v[22:25], v[172:175], v[200:203], v[22:25]
	v_mfma_f32_16x16x32_bf16 v[18:21], v[176:179], v[200:203], v[18:21]
	v_mfma_f32_16x16x32_bf16 v[6:9], v[172:175], v[208:211], v[6:9]
	v_mfma_f32_16x16x32_bf16 v[2:5], v[176:179], v[208:211], v[2:5]
	s_setprio 0
	s_barrier
	s_add_i32 s20, 0, 0x18000
	v_add_u32_e32 v147, s20, v1
	s_add_i32 s21, 0, 0x1c000
	ds_read_b128 v[148:151], v147
	ds_read_b128 v[152:155], v147 offset:256
	ds_read_b128 v[156:159], v147 offset:8192
	ds_read_b128 v[160:163], v147 offset:8448
	v_add_u32_e32 v147, s21, v1
	ds_read_b128 v[164:167], v147
	ds_read_b128 v[168:171], v147 offset:256
	ds_read_b128 v[172:175], v147 offset:8192
	ds_read_b128 v[176:179], v147 offset:8448
	s_add_u32 s2, s4, 0x104000
	s_addc_u32 s3, s5, 0
	s_mov_b32 m0, s41
	ds_read_b128 v[180:183], v145 offset:32768
	ds_read_b128 v[184:187], v145 offset:33792
	ds_read_b128 v[188:191], v145 offset:34816
	ds_read_b128 v[192:195], v145 offset:35840
	ds_read_b128 v[196:199], v145 offset:36864
	ds_read_b128 v[200:203], v145 offset:37888
	ds_read_b128 v[204:207], v145 offset:38912
	global_load_lds_dwordx4 v130, s[2:3]
	s_mov_b32 m0, s76
	ds_read_b128 v[208:211], v145 offset:39936
	global_load_lds_dwordx4 v134, s[2:3]
	s_waitcnt vmcnt(8)
	s_waitcnt lgkmcnt(0)
	s_barrier
	s_setprio 1
	s_waitcnt lgkmcnt(0)
	v_mfma_f32_16x16x32_bf16 v[126:129], v[148:151], v[180:183], v[126:129]
	v_mfma_f32_16x16x32_bf16 v[122:125], v[152:155], v[180:183], v[122:125]
	v_mfma_f32_16x16x32_bf16 v[110:113], v[148:151], v[188:191], v[110:113]
	v_mfma_f32_16x16x32_bf16 v[106:109], v[152:155], v[188:191], v[106:109]
	v_mfma_f32_16x16x32_bf16 v[94:97], v[148:151], v[196:199], v[94:97]
	v_mfma_f32_16x16x32_bf16 v[90:93], v[152:155], v[196:199], v[90:93]
	v_mfma_f32_16x16x32_bf16 v[78:81], v[148:151], v[204:207], v[78:81]
	v_mfma_f32_16x16x32_bf16 v[74:77], v[152:155], v[204:207], v[74:77]
	v_mfma_f32_16x16x32_bf16 v[126:129], v[156:159], v[184:187], v[126:129]
	v_mfma_f32_16x16x32_bf16 v[122:125], v[160:163], v[184:187], v[122:125]
	v_mfma_f32_16x16x32_bf16 v[110:113], v[156:159], v[192:195], v[110:113]
	v_mfma_f32_16x16x32_bf16 v[106:109], v[160:163], v[192:195], v[106:109]
	v_mfma_f32_16x16x32_bf16 v[94:97], v[156:159], v[200:203], v[94:97]
	v_mfma_f32_16x16x32_bf16 v[90:93], v[160:163], v[200:203], v[90:93]
	v_mfma_f32_16x16x32_bf16 v[78:81], v[156:159], v[208:211], v[78:81]
	v_mfma_f32_16x16x32_bf16 v[74:77], v[160:163], v[208:211], v[74:77]
	s_setprio 0
	s_setprio 1
	v_mfma_f32_16x16x32_bf16 v[118:121], v[164:167], v[180:183], v[118:121]
	v_mfma_f32_16x16x32_bf16 v[114:117], v[168:171], v[180:183], v[114:117]
	v_mfma_f32_16x16x32_bf16 v[102:105], v[164:167], v[188:191], v[102:105]
	v_mfma_f32_16x16x32_bf16 v[98:101], v[168:171], v[188:191], v[98:101]
	v_mfma_f32_16x16x32_bf16 v[86:89], v[164:167], v[196:199], v[86:89]
	v_mfma_f32_16x16x32_bf16 v[82:85], v[168:171], v[196:199], v[82:85]
	v_mfma_f32_16x16x32_bf16 v[70:73], v[164:167], v[204:207], v[70:73]
	v_mfma_f32_16x16x32_bf16 v[66:69], v[168:171], v[204:207], v[66:69]
	v_mfma_f32_16x16x32_bf16 v[118:121], v[172:175], v[184:187], v[118:121]
	v_mfma_f32_16x16x32_bf16 v[114:117], v[176:179], v[184:187], v[114:117]
	v_mfma_f32_16x16x32_bf16 v[102:105], v[172:175], v[192:195], v[102:105]
	v_mfma_f32_16x16x32_bf16 v[98:101], v[176:179], v[192:195], v[98:101]
	v_mfma_f32_16x16x32_bf16 v[86:89], v[172:175], v[200:203], v[86:89]
	v_mfma_f32_16x16x32_bf16 v[82:85], v[176:179], v[200:203], v[82:85]
	v_mfma_f32_16x16x32_bf16 v[70:73], v[172:175], v[208:211], v[70:73]
	v_mfma_f32_16x16x32_bf16 v[66:69], v[176:179], v[208:211], v[66:69]
	s_setprio 0
	s_barrier
	s_add_i32 s2, s20, s18
	s_mov_b32 m0, s2
	ds_read_b128 v[180:183], v145 offset:49152
	ds_read_b128 v[184:187], v145 offset:50176
	ds_read_b128 v[188:191], v145 offset:51200
	ds_read_b128 v[192:195], v145 offset:52224
	global_load_lds_dwordx4 v132, s[62:63]
	s_add_i32 m0, s2, 0x2000
	s_add_u32 s2, s60, 0x209000
	s_addc_u32 s3, s61, 0
	s_add_i32 s4, s21, s18
	global_load_lds_dwordx4 v136, s[62:63]
	s_mov_b32 m0, s4
	ds_read_b128 v[196:199], v145 offset:53248
	global_load_lds_dwordx4 v132, s[2:3]
	s_add_i32 m0, s4, 0x2000
	ds_read_b128 v[200:203], v145 offset:54272
	global_load_lds_dwordx4 v136, s[2:3]
	s_mov_b32 m0, s77
	ds_read_b128 v[204:207], v145 offset:55296
	global_load_lds_dwordx4 v130, s[100:101]
	s_mov_b32 m0, s78
	ds_read_b128 v[208:211], v145 offset:56320
	global_load_lds_dwordx4 v134, s[100:101]
	s_waitcnt vmcnt(8)
	s_waitcnt lgkmcnt(0)
	s_barrier
	s_setprio 1
	s_waitcnt lgkmcnt(0)
	v_mfma_f32_16x16x32_bf16 v[62:65], v[148:151], v[180:183], v[62:65]
	v_mfma_f32_16x16x32_bf16 v[58:61], v[152:155], v[180:183], v[58:61]
	v_mfma_f32_16x16x32_bf16 v[46:49], v[148:151], v[188:191], v[46:49]
	v_mfma_f32_16x16x32_bf16 v[42:45], v[152:155], v[188:191], v[42:45]
	v_mfma_f32_16x16x32_bf16 v[30:33], v[148:151], v[196:199], v[30:33]
	v_mfma_f32_16x16x32_bf16 v[26:29], v[152:155], v[196:199], v[26:29]
	v_mfma_f32_16x16x32_bf16 v[14:17], v[148:151], v[204:207], v[14:17]
	v_mfma_f32_16x16x32_bf16 v[10:13], v[152:155], v[204:207], v[10:13]
	v_mfma_f32_16x16x32_bf16 v[62:65], v[156:159], v[184:187], v[62:65]
	v_mfma_f32_16x16x32_bf16 v[58:61], v[160:163], v[184:187], v[58:61]
	v_mfma_f32_16x16x32_bf16 v[46:49], v[156:159], v[192:195], v[46:49]
	v_mfma_f32_16x16x32_bf16 v[42:45], v[160:163], v[192:195], v[42:45]
	v_mfma_f32_16x16x32_bf16 v[30:33], v[156:159], v[200:203], v[30:33]
	v_mfma_f32_16x16x32_bf16 v[26:29], v[160:163], v[200:203], v[26:29]
	v_mfma_f32_16x16x32_bf16 v[14:17], v[156:159], v[208:211], v[14:17]
	v_mfma_f32_16x16x32_bf16 v[10:13], v[160:163], v[208:211], v[10:13]
	s_setprio 0
	s_setprio 1
	v_mfma_f32_16x16x32_bf16 v[54:57], v[164:167], v[180:183], v[54:57]
	v_mfma_f32_16x16x32_bf16 v[50:53], v[168:171], v[180:183], v[50:53]
	v_mfma_f32_16x16x32_bf16 v[38:41], v[164:167], v[188:191], v[38:41]
	v_mfma_f32_16x16x32_bf16 v[34:37], v[168:171], v[188:191], v[34:37]
	v_mfma_f32_16x16x32_bf16 v[22:25], v[164:167], v[196:199], v[22:25]
	v_mfma_f32_16x16x32_bf16 v[18:21], v[168:171], v[196:199], v[18:21]
	v_mfma_f32_16x16x32_bf16 v[6:9], v[164:167], v[204:207], v[6:9]
	v_mfma_f32_16x16x32_bf16 v[2:5], v[168:171], v[204:207], v[2:5]
	v_mfma_f32_16x16x32_bf16 v[54:57], v[172:175], v[184:187], v[54:57]
	v_mfma_f32_16x16x32_bf16 v[50:53], v[176:179], v[184:187], v[50:53]
	v_mfma_f32_16x16x32_bf16 v[38:41], v[172:175], v[192:195], v[38:41]
	v_mfma_f32_16x16x32_bf16 v[34:37], v[176:179], v[192:195], v[34:37]
	v_mfma_f32_16x16x32_bf16 v[22:25], v[172:175], v[200:203], v[22:25]
	v_mfma_f32_16x16x32_bf16 v[18:21], v[176:179], v[200:203], v[18:21]
	v_mfma_f32_16x16x32_bf16 v[6:9], v[172:175], v[208:211], v[6:9]
	v_mfma_f32_16x16x32_bf16 v[2:5], v[176:179], v[208:211], v[2:5]
	s_setprio 0
	s_barrier
	s_add_i32 s2, s90, 2
	s_cmp_gt_u32 s90, 61
	s_cbranch_scc1 .LBB0_802
	s_mov_b32 s90, s2
	s_branch .LBB0_767

.LBB0_933:
	s_lshl_b32 s2, s88, 7
	s_add_u32 s26, s34, s2
	s_addc_u32 s27, s35, 0
	s_add_u32 s46, s26, 0x100
	s_addc_u32 s47, s27, 0
	s_and_b64 s[2:3], s[44:45], exec
	v_add_u32_e32 v187, s36, v182
	s_mul_i32 s2, s88, 0x88800
	ds_read_b128 v[128:131], v187
	ds_read_b128 v[132:135], v187 offset:256
	ds_read_b128 v[178:181], v187 offset:8192
	ds_read_b128 v[188:191], v187 offset:8448
	v_add_u32_e32 v187, s37, v182
	s_cselect_b32 s51, s47, s23
	s_cselect_b32 s50, s46, s22
	s_add_u32 s2, s40, s2
	ds_read_b128 v[192:195], v187
	ds_read_b128 v[196:199], v187 offset:256
	ds_read_b128 v[200:203], v187 offset:8192
	ds_read_b128 v[204:207], v187 offset:8448
	s_addc_u32 s3, s41, 0
	s_add_u32 s46, s2, 0x111000
	s_addc_u32 s47, s3, 0
	s_and_b64 s[2:3], s[44:45], exec
	s_cselect_b32 s44, s46, s87
	s_cselect_b32 s45, s47, s21
	s_add_u32 s46, s44, 0x88800
	s_addc_u32 s47, s45, 0
	s_add_u32 s2, s26, 0x404080
	s_addc_u32 s3, s27, 0
	s_add_u32 s98, s44, s4
	s_addc_u32 s99, s45, s5
	s_add_u32 s100, s50, s12
	s_addc_u32 s101, s51, s13
	s_add_i32 m0, s33, 0xc000
	ds_read_b128 v[208:211], v185
	ds_read_b128 v[212:215], v185 offset:1024
	ds_read_b128 v[216:219], v185 offset:2048
	ds_read_b128 v[220:223], v185 offset:3072
	ds_read_b128 v[224:227], v185 offset:4096
	ds_read_b128 v[228:231], v185 offset:5120
	ds_read_b128 v[232:235], v185 offset:6144
	global_load_lds_dwordx4 v136, s[2:3]
	s_add_i32 m0, s33, 0xe000
	ds_read_b128 v[236:239], v185 offset:7168
	global_load_lds_dwordx4 v140, s[2:3]
	s_waitcnt vmcnt(8)
	s_waitcnt lgkmcnt(0)
	s_barrier
	s_setprio 1
	s_waitcnt lgkmcnt(0)
	v_mfma_f32_16x16x32_bf16 v[124:127], v[128:131], v[208:211], v[124:127]
	v_mfma_f32_16x16x32_bf16 v[120:123], v[132:135], v[208:211], v[120:123]
	v_mfma_f32_16x16x32_bf16 v[108:111], v[128:131], v[216:219], v[108:111]
	v_mfma_f32_16x16x32_bf16 v[104:107], v[132:135], v[216:219], v[104:107]
	v_mfma_f32_16x16x32_bf16 v[92:95], v[128:131], v[224:227], v[92:95]
	v_mfma_f32_16x16x32_bf16 v[88:91], v[132:135], v[224:227], v[88:91]
	v_mfma_f32_16x16x32_bf16 v[76:79], v[128:131], v[232:235], v[76:79]
	v_mfma_f32_16x16x32_bf16 v[72:75], v[132:135], v[232:235], v[72:75]
	v_mfma_f32_16x16x32_bf16 v[124:127], v[178:181], v[212:215], v[124:127]
	v_mfma_f32_16x16x32_bf16 v[120:123], v[188:191], v[212:215], v[120:123]
	v_mfma_f32_16x16x32_bf16 v[108:111], v[178:181], v[220:223], v[108:111]
	v_mfma_f32_16x16x32_bf16 v[104:107], v[188:191], v[220:223], v[104:107]
	v_mfma_f32_16x16x32_bf16 v[92:95], v[178:181], v[228:231], v[92:95]
	v_mfma_f32_16x16x32_bf16 v[88:91], v[188:191], v[228:231], v[88:91]
	v_mfma_f32_16x16x32_bf16 v[76:79], v[178:181], v[236:239], v[76:79]
	v_mfma_f32_16x16x32_bf16 v[72:75], v[188:191], v[236:239], v[72:75]
	s_setprio 0
	s_setprio 1
	v_mfma_f32_16x16x32_bf16 v[116:119], v[192:195], v[208:211], v[116:119]
	v_mfma_f32_16x16x32_bf16 v[112:115], v[196:199], v[208:211], v[112:115]
	v_mfma_f32_16x16x32_bf16 v[100:103], v[192:195], v[216:219], v[100:103]
	v_mfma_f32_16x16x32_bf16 v[96:99], v[196:199], v[216:219], v[96:99]
	v_mfma_f32_16x16x32_bf16 v[84:87], v[192:195], v[224:227], v[84:87]
	v_mfma_f32_16x16x32_bf16 v[80:83], v[196:199], v[224:227], v[80:83]
	v_mfma_f32_16x16x32_bf16 v[68:71], v[192:195], v[232:235], v[68:71]
	v_mfma_f32_16x16x32_bf16 v[64:67], v[196:199], v[232:235], v[64:67]
	v_mfma_f32_16x16x32_bf16 v[116:119], v[200:203], v[212:215], v[116:119]
	v_mfma_f32_16x16x32_bf16 v[112:115], v[204:207], v[212:215], v[112:115]
	v_mfma_f32_16x16x32_bf16 v[100:103], v[200:203], v[220:223], v[100:103]
	v_mfma_f32_16x16x32_bf16 v[96:99], v[204:207], v[220:223], v[96:99]
	v_mfma_f32_16x16x32_bf16 v[84:87], v[200:203], v[228:231], v[84:87]
	v_mfma_f32_16x16x32_bf16 v[80:83], v[204:207], v[228:231], v[80:83]
	v_mfma_f32_16x16x32_bf16 v[68:71], v[200:203], v[236:239], v[68:71]
	v_mfma_f32_16x16x32_bf16 v[64:67], v[204:207], v[236:239], v[64:67]
	s_setprio 0
	s_barrier
	s_add_i32 s2, s36, s31
	s_mov_b32 m0, s2
	ds_read_b128 v[208:211], v185 offset:16384
	ds_read_b128 v[212:215], v185 offset:17408
	ds_read_b128 v[216:219], v185 offset:18432
	ds_read_b128 v[220:223], v185 offset:19456
	global_load_lds_dwordx4 v138, s[44:45]
	s_add_i32 m0, s2, 0x2000
	s_add_i32 s2, s37, s31
	global_load_lds_dwordx4 v142, s[44:45]
	s_mov_b32 m0, s2
	ds_read_b128 v[224:227], v185 offset:20480
	global_load_lds_dwordx4 v138, s[98:99]
	s_add_i32 m0, s2, 0x2000
	ds_read_b128 v[228:231], v185 offset:21504
	global_load_lds_dwordx4 v142, s[98:99]
	s_mov_b32 m0, s33
	ds_read_b128 v[232:235], v185 offset:22528
	global_load_lds_dwordx4 v136, s[50:51]
	s_mov_b32 m0, s72
	ds_read_b128 v[236:239], v185 offset:23552
	global_load_lds_dwordx4 v140, s[50:51]
	s_waitcnt vmcnt(8)
	s_waitcnt lgkmcnt(0)
	s_barrier
	s_setprio 1
	s_waitcnt lgkmcnt(0)
	v_mfma_f32_16x16x32_bf16 v[60:63], v[128:131], v[208:211], v[60:63]
	v_mfma_f32_16x16x32_bf16 v[56:59], v[132:135], v[208:211], v[56:59]
	v_mfma_f32_16x16x32_bf16 v[44:47], v[128:131], v[216:219], v[44:47]
	v_mfma_f32_16x16x32_bf16 v[40:43], v[132:135], v[216:219], v[40:43]
	v_mfma_f32_16x16x32_bf16 v[28:31], v[128:131], v[224:227], v[28:31]
	v_mfma_f32_16x16x32_bf16 v[24:27], v[132:135], v[224:227], v[24:27]
	v_mfma_f32_16x16x32_bf16 v[12:15], v[128:131], v[232:235], v[12:15]
	v_mfma_f32_16x16x32_bf16 v[8:11], v[132:135], v[232:235], v[8:11]
	v_mfma_f32_16x16x32_bf16 v[60:63], v[178:181], v[212:215], v[60:63]
	v_mfma_f32_16x16x32_bf16 v[56:59], v[188:191], v[212:215], v[56:59]
	v_mfma_f32_16x16x32_bf16 v[44:47], v[178:181], v[220:223], v[44:47]
	v_mfma_f32_16x16x32_bf16 v[40:43], v[188:191], v[220:223], v[40:43]
	v_mfma_f32_16x16x32_bf16 v[28:31], v[178:181], v[228:231], v[28:31]
	v_mfma_f32_16x16x32_bf16 v[24:27], v[188:191], v[228:231], v[24:27]
	v_mfma_f32_16x16x32_bf16 v[12:15], v[178:181], v[236:239], v[12:15]
	v_mfma_f32_16x16x32_bf16 v[8:11], v[188:191], v[236:239], v[8:11]
	s_setprio 0
	s_setprio 1
	v_mfma_f32_16x16x32_bf16 v[52:55], v[192:195], v[208:211], v[52:55]
	v_mfma_f32_16x16x32_bf16 v[48:51], v[196:199], v[208:211], v[48:51]
	v_mfma_f32_16x16x32_bf16 v[36:39], v[192:195], v[216:219], v[36:39]
	v_mfma_f32_16x16x32_bf16 v[32:35], v[196:199], v[216:219], v[32:35]
	v_mfma_f32_16x16x32_bf16 v[20:23], v[192:195], v[224:227], v[20:23]
	v_mfma_f32_16x16x32_bf16 v[16:19], v[196:199], v[224:227], v[16:19]
	v_mfma_f32_16x16x32_bf16 v[4:7], v[192:195], v[232:235], v[4:7]
	v_mfma_f32_16x16x32_bf16 v[0:3], v[196:199], v[232:235], v[0:3]
	v_mfma_f32_16x16x32_bf16 v[52:55], v[200:203], v[212:215], v[52:55]
	v_mfma_f32_16x16x32_bf16 v[48:51], v[204:207], v[212:215], v[48:51]
	v_mfma_f32_16x16x32_bf16 v[36:39], v[200:203], v[220:223], v[36:39]
	v_mfma_f32_16x16x32_bf16 v[32:35], v[204:207], v[220:223], v[32:35]
	v_mfma_f32_16x16x32_bf16 v[20:23], v[200:203], v[228:231], v[20:23]
	v_mfma_f32_16x16x32_bf16 v[16:19], v[204:207], v[228:231], v[16:19]
	v_mfma_f32_16x16x32_bf16 v[4:7], v[200:203], v[236:239], v[4:7]
	v_mfma_f32_16x16x32_bf16 v[0:3], v[204:207], v[236:239], v[0:3]
	s_setprio 0
	s_barrier
	s_add_i32 s26, 0, 0x18000
	v_add_u32_e32 v187, s26, v182
	s_add_i32 s27, 0, 0x1c000
	ds_read_b128 v[128:131], v187
	ds_read_b128 v[132:135], v187 offset:256
	ds_read_b128 v[178:181], v187 offset:8192
	ds_read_b128 v[188:191], v187 offset:8448
	v_add_u32_e32 v187, s27, v182
	ds_read_b128 v[192:195], v187
	ds_read_b128 v[196:199], v187 offset:256
	ds_read_b128 v[200:203], v187 offset:8192
	ds_read_b128 v[204:207], v187 offset:8448
	s_add_u32 s2, s50, 0x404000
	s_addc_u32 s3, s51, 0
	s_mov_b32 m0, s73
	ds_read_b128 v[208:211], v185 offset:32768
	ds_read_b128 v[212:215], v185 offset:33792
	ds_read_b128 v[216:219], v185 offset:34816
	ds_read_b128 v[220:223], v185 offset:35840
	ds_read_b128 v[224:227], v185 offset:36864
	ds_read_b128 v[228:231], v185 offset:37888
	ds_read_b128 v[232:235], v185 offset:38912
	global_load_lds_dwordx4 v136, s[2:3]
	s_mov_b32 m0, s74
	ds_read_b128 v[236:239], v185 offset:39936
	global_load_lds_dwordx4 v140, s[2:3]
	s_waitcnt vmcnt(8)
	s_waitcnt lgkmcnt(0)
	s_barrier
	s_setprio 1
	s_waitcnt lgkmcnt(0)
	v_mfma_f32_16x16x32_bf16 v[124:127], v[128:131], v[208:211], v[124:127]
	v_mfma_f32_16x16x32_bf16 v[120:123], v[132:135], v[208:211], v[120:123]
	v_mfma_f32_16x16x32_bf16 v[108:111], v[128:131], v[216:219], v[108:111]
	v_mfma_f32_16x16x32_bf16 v[104:107], v[132:135], v[216:219], v[104:107]
	v_mfma_f32_16x16x32_bf16 v[92:95], v[128:131], v[224:227], v[92:95]
	v_mfma_f32_16x16x32_bf16 v[88:91], v[132:135], v[224:227], v[88:91]
	v_mfma_f32_16x16x32_bf16 v[76:79], v[128:131], v[232:235], v[76:79]
	v_mfma_f32_16x16x32_bf16 v[72:75], v[132:135], v[232:235], v[72:75]
	v_mfma_f32_16x16x32_bf16 v[124:127], v[178:181], v[212:215], v[124:127]
	v_mfma_f32_16x16x32_bf16 v[120:123], v[188:191], v[212:215], v[120:123]
	v_mfma_f32_16x16x32_bf16 v[108:111], v[178:181], v[220:223], v[108:111]
	v_mfma_f32_16x16x32_bf16 v[104:107], v[188:191], v[220:223], v[104:107]
	v_mfma_f32_16x16x32_bf16 v[92:95], v[178:181], v[228:231], v[92:95]
	v_mfma_f32_16x16x32_bf16 v[88:91], v[188:191], v[228:231], v[88:91]
	v_mfma_f32_16x16x32_bf16 v[76:79], v[178:181], v[236:239], v[76:79]
	v_mfma_f32_16x16x32_bf16 v[72:75], v[188:191], v[236:239], v[72:75]
	s_setprio 0
	s_setprio 1
	v_mfma_f32_16x16x32_bf16 v[116:119], v[192:195], v[208:211], v[116:119]
	v_mfma_f32_16x16x32_bf16 v[112:115], v[196:199], v[208:211], v[112:115]
	v_mfma_f32_16x16x32_bf16 v[100:103], v[192:195], v[216:219], v[100:103]
	v_mfma_f32_16x16x32_bf16 v[96:99], v[196:199], v[216:219], v[96:99]
	v_mfma_f32_16x16x32_bf16 v[84:87], v[192:195], v[224:227], v[84:87]
	v_mfma_f32_16x16x32_bf16 v[80:83], v[196:199], v[224:227], v[80:83]
	v_mfma_f32_16x16x32_bf16 v[68:71], v[192:195], v[232:235], v[68:71]
	v_mfma_f32_16x16x32_bf16 v[64:67], v[196:199], v[232:235], v[64:67]
	v_mfma_f32_16x16x32_bf16 v[116:119], v[200:203], v[212:215], v[116:119]
	v_mfma_f32_16x16x32_bf16 v[112:115], v[204:207], v[212:215], v[112:115]
	v_mfma_f32_16x16x32_bf16 v[100:103], v[200:203], v[220:223], v[100:103]
	v_mfma_f32_16x16x32_bf16 v[96:99], v[204:207], v[220:223], v[96:99]
	v_mfma_f32_16x16x32_bf16 v[84:87], v[200:203], v[228:231], v[84:87]
	v_mfma_f32_16x16x32_bf16 v[80:83], v[204:207], v[228:231], v[80:83]
	v_mfma_f32_16x16x32_bf16 v[68:71], v[200:203], v[236:239], v[68:71]
	v_mfma_f32_16x16x32_bf16 v[64:67], v[204:207], v[236:239], v[64:67]
	s_setprio 0
	s_barrier
	s_add_i32 s2, s26, s31
	s_mov_b32 m0, s2
	ds_read_b128 v[208:211], v185 offset:49152
	ds_read_b128 v[212:215], v185 offset:50176
	ds_read_b128 v[216:219], v185 offset:51200
	ds_read_b128 v[220:223], v185 offset:52224
	global_load_lds_dwordx4 v138, s[46:47]
	s_add_i32 m0, s2, 0x2000
	s_add_u32 s2, s44, 0x89000
	s_addc_u32 s3, s45, 0
	s_add_i32 s26, s27, s31
	global_load_lds_dwordx4 v142, s[46:47]
	s_mov_b32 m0, s26
	ds_read_b128 v[224:227], v185 offset:53248
	global_load_lds_dwordx4 v138, s[2:3]
	s_add_i32 m0, s26, 0x2000
	ds_read_b128 v[228:231], v185 offset:54272
	global_load_lds_dwordx4 v142, s[2:3]
	s_mov_b32 m0, s78
	ds_read_b128 v[232:235], v185 offset:55296
	global_load_lds_dwordx4 v136, s[100:101]
	s_mov_b32 m0, s79
	ds_read_b128 v[236:239], v185 offset:56320
	global_load_lds_dwordx4 v140, s[100:101]
	s_waitcnt vmcnt(8)
	s_waitcnt lgkmcnt(0)
	s_barrier
	s_setprio 1
	s_waitcnt lgkmcnt(0)
	v_mfma_f32_16x16x32_bf16 v[60:63], v[128:131], v[208:211], v[60:63]
	v_mfma_f32_16x16x32_bf16 v[56:59], v[132:135], v[208:211], v[56:59]
	v_mfma_f32_16x16x32_bf16 v[44:47], v[128:131], v[216:219], v[44:47]
	v_mfma_f32_16x16x32_bf16 v[40:43], v[132:135], v[216:219], v[40:43]
	v_mfma_f32_16x16x32_bf16 v[28:31], v[128:131], v[224:227], v[28:31]
	v_mfma_f32_16x16x32_bf16 v[24:27], v[132:135], v[224:227], v[24:27]
	v_mfma_f32_16x16x32_bf16 v[12:15], v[128:131], v[232:235], v[12:15]
	v_mfma_f32_16x16x32_bf16 v[8:11], v[132:135], v[232:235], v[8:11]
	v_mfma_f32_16x16x32_bf16 v[60:63], v[178:181], v[212:215], v[60:63]
	v_mfma_f32_16x16x32_bf16 v[56:59], v[188:191], v[212:215], v[56:59]
	v_mfma_f32_16x16x32_bf16 v[44:47], v[178:181], v[220:223], v[44:47]
	v_mfma_f32_16x16x32_bf16 v[40:43], v[188:191], v[220:223], v[40:43]
	v_mfma_f32_16x16x32_bf16 v[28:31], v[178:181], v[228:231], v[28:31]
	v_mfma_f32_16x16x32_bf16 v[24:27], v[188:191], v[228:231], v[24:27]
	v_mfma_f32_16x16x32_bf16 v[12:15], v[178:181], v[236:239], v[12:15]
	v_mfma_f32_16x16x32_bf16 v[8:11], v[188:191], v[236:239], v[8:11]
	s_setprio 0
	s_setprio 1
	v_mfma_f32_16x16x32_bf16 v[52:55], v[192:195], v[208:211], v[52:55]
	v_mfma_f32_16x16x32_bf16 v[48:51], v[196:199], v[208:211], v[48:51]
	v_mfma_f32_16x16x32_bf16 v[36:39], v[192:195], v[216:219], v[36:39]
	v_mfma_f32_16x16x32_bf16 v[32:35], v[196:199], v[216:219], v[32:35]
	v_mfma_f32_16x16x32_bf16 v[20:23], v[192:195], v[224:227], v[20:23]
	v_mfma_f32_16x16x32_bf16 v[16:19], v[196:199], v[224:227], v[16:19]
	v_mfma_f32_16x16x32_bf16 v[4:7], v[192:195], v[232:235], v[4:7]
	v_mfma_f32_16x16x32_bf16 v[0:3], v[196:199], v[232:235], v[0:3]
	v_mfma_f32_16x16x32_bf16 v[52:55], v[200:203], v[212:215], v[52:55]
	v_mfma_f32_16x16x32_bf16 v[48:51], v[204:207], v[212:215], v[48:51]
	v_mfma_f32_16x16x32_bf16 v[36:39], v[200:203], v[220:223], v[36:39]
	v_mfma_f32_16x16x32_bf16 v[32:35], v[204:207], v[220:223], v[32:35]
	v_mfma_f32_16x16x32_bf16 v[20:23], v[200:203], v[228:231], v[20:23]
	v_mfma_f32_16x16x32_bf16 v[16:19], v[204:207], v[228:231], v[16:19]
	v_mfma_f32_16x16x32_bf16 v[4:7], v[200:203], v[236:239], v[4:7]
	v_mfma_f32_16x16x32_bf16 v[0:3], v[204:207], v[236:239], v[0:3]
	s_setprio 0
	s_barrier
	s_add_i32 s2, s88, 2
	s_cmpk_gt_u32 s88, 0xfd
	s_cbranch_scc1 .LBB0_939
	s_mov_b32 s88, s2
	s_branch .LBB0_904
